# v22 + removed unneeded s_nop 4 (SALU-written bases) in the MLA loop LDS-DMA blocks
# speedup vs baseline: 1.0028x; 1.0028x over previous
.LBB0_1473:
	v_mov_b64_e32 v[32:33], v[16:17]
	v_mov_b64_e32 v[30:31], v[14:15]
	v_mov_b64_e32 v[28:29], v[12:13]
	v_mov_b64_e32 v[26:27], v[10:11]
	v_mov_b64_e32 v[24:25], v[8:9]
	v_mov_b64_e32 v[22:23], v[6:7]
	v_mov_b64_e32 v[20:21], v[4:5]
	v_mov_b64_e32 v[18:19], v[2:3]
	s_waitcnt vmcnt(0) lgkmcnt(0)
	s_barrier
	s_waitcnt vmcnt(0)
	ds_write_b128 v190, v[98:101]
	ds_write_b128 v190, v[106:109] offset:1024
	ds_write_b128 v190, v[102:105] offset:2048
	ds_write_b128 v190, v[114:117] offset:3072
	ds_write_b128 v190, v[110:113] offset:4096
	ds_write_b128 v190, v[118:121] offset:5120
	v_add_u32_e32 v34, v185, v184
	s_mul_i32 s8, s49, 0x3000
	v_add_u32_e32 v35, v185, v189
	ds_read_b128 v[98:101], v34
	ds_read_b128 v[102:105], v34 offset:2048
	ds_read_b128 v[106:109], v35
	ds_read_b128 v[110:113], v34 offset:4096
	ds_read_b128 v[114:117], v35 offset:2048
	ds_read_b128 v[118:121], v35 offset:4096
	v_add_u32_e32 v34, s8, v182
	v_add_u32_e32 v35, v34, v184
	v_add_u32_e32 v34, v34, v189
	ds_read_b128 v[94:97], v35
	ds_read_b128 v[86:89], v35 offset:2048
	ds_read_b128 v[90:93], v34
	ds_read_b128 v[82:85], v34 offset:2048
	ds_read_b128 v[78:81], v35 offset:4096
	ds_read_b128 v[74:77], v35 offset:6144
	ds_read_b128 v[70:73], v34 offset:4096
	ds_read_b128 v[66:69], v34 offset:6144
	ds_read_b128 v[62:65], v35 offset:8192
	ds_read_b128 v[58:61], v35 offset:10240
	ds_read_b128 v[54:57], v34 offset:8192
	ds_read_b128 v[50:53], v34 offset:10240
	s_lshl_b64 s[18:19], s[0:1], 1
	s_add_u32 s26, s10, s18
	s_addc_u32 s27, s11, s19
	s_or_b32 s24, s14, 64
	s_mov_b32 s25, s15
	s_lshl_b64 s[22:23], s[24:25], 9
	s_lshl_b64 s[8:9], s[24:25], 10
	s_add_u32 s52, s26, s8
	s_addc_u32 s53, s27, s9
	s_xor_b32 s51, s49, 1
	s_mul_i32 s0, s51, 0x3000
	s_add_i32 s54, s0, s38
	s_mov_b32 s55, m0
	s_mov_b32 m0, s54
	s_nop 0
	global_load_lds_dwordx4 v1, s[52:53]
	s_mov_b32 m0, s55
	v_cndmask_b32_e64 v34, 0, 1, s[4:5]
	v_cmp_ne_u32_e64 s[8:9], 1, v34
	s_andn2_b64 vcc, exec, s[4:5]
	s_cbranch_vccnz .LBB0_1475
	s_lshl_b64 s[24:25], s[24:25], 6
	s_add_u32 s24, s16, s24
	s_addc_u32 s25, s17, s25
	s_add_i32 s0, s0, s39
	s_mov_b32 s52, m0
	s_mov_b32 m0, s0
	s_nop 0
	global_load_lds_dwordx4 v180, s[24:25]
	s_mov_b32 m0, s52
.LBB0_1475:
	s_add_u32 s0, s34, s18
	s_addc_u32 s24, s35, s19
	s_lshl_b64 s[22:23], s[22:23], 1
	s_add_u32 s22, s0, s22
	s_addc_u32 s23, s24, s23
	s_lshl_b32 s25, s51, 13
	s_add_i32 s25, s25, s43
	s_mov_b32 s52, m0
	s_mov_b32 m0, s25
	s_nop 0
	global_load_lds_dwordx4 v181, s[22:23]
	s_mov_b32 m0, s52
	s_waitcnt lgkmcnt(11)
	v_mfma_f32_32x32x16_bf16 v[34:49], v[94:97], v[98:101], v[18:33]
	s_waitcnt lgkmcnt(10)
	v_mfma_f32_32x32x16_bf16 v[18:33], v[86:89], v[98:101], v[18:33]
	s_waitcnt lgkmcnt(9)
	v_mfma_f32_32x32x16_bf16 v[34:49], v[90:93], v[106:109], v[34:49]
	s_waitcnt lgkmcnt(8)
	v_mfma_f32_32x32x16_bf16 v[18:33], v[82:85], v[106:109], v[18:33]
	s_waitcnt lgkmcnt(7)
	v_mfma_f32_32x32x16_bf16 v[34:49], v[78:81], v[102:105], v[34:49]
	s_waitcnt lgkmcnt(6)
	v_mfma_f32_32x32x16_bf16 v[18:33], v[74:77], v[102:105], v[18:33]
	s_waitcnt lgkmcnt(5)
	v_mfma_f32_32x32x16_bf16 v[34:49], v[70:73], v[114:117], v[34:49]
	s_waitcnt lgkmcnt(4)
	v_mfma_f32_32x32x16_bf16 v[18:33], v[66:69], v[114:117], v[18:33]
	s_waitcnt lgkmcnt(3)
	v_mfma_f32_32x32x16_bf16 v[34:49], v[62:65], v[110:113], v[34:49]
	v_lshl_add_u32 v62, s49, 13, v183
	ds_read_b64_tr_b16 v[94:95], v62 offset:24576
	ds_read_b64_tr_b16 v[96:97], v62 offset:25088
	ds_read_b64_tr_b16 v[90:91], v62 offset:25600
	ds_read_b64_tr_b16 v[92:93], v62 offset:26112
	ds_read_b64_tr_b16 v[86:87], v62 offset:26624
	ds_read_b64_tr_b16 v[88:89], v62 offset:27136
	ds_read_b64_tr_b16 v[82:83], v62 offset:27648
	ds_read_b64_tr_b16 v[84:85], v62 offset:28160
	ds_read_b64_tr_b16 v[78:79], v62 offset:28672
	ds_read_b64_tr_b16 v[80:81], v62 offset:29184
	ds_read_b64_tr_b16 v[74:75], v62 offset:29696
	ds_read_b64_tr_b16 v[76:77], v62 offset:30208
	ds_read_b64_tr_b16 v[70:71], v62 offset:30720
	ds_read_b64_tr_b16 v[72:73], v62 offset:31232
	ds_read_b64_tr_b16 v[66:67], v62 offset:31744
	ds_read_b64_tr_b16 v[68:69], v62 offset:32256
	s_waitcnt lgkmcnt(14)
	v_mfma_f32_32x32x16_bf16 v[18:33], v[58:61], v[110:113], v[18:33]
	v_mfma_f32_32x32x16_bf16 v[34:49], v[54:57], v[118:121], v[34:49]
	v_mfma_f32_32x32x16_bf16 v[18:33], v[50:53], v[118:121], v[18:33]
	s_nop 10
	v_max_f32_e32 v50, v35, v35
	v_max_f32_e32 v51, v34, v34
	v_max_f32_e32 v50, v51, v50
	v_max3_f32 v51, v36, v37, v19
	v_max3_f32 v50, v50, v18, v20
	v_max3_f32 v50, v50, v21, v38
	v_max3_f32 v51, v51, v40, v41
	v_max3_f32 v50, v50, v39, v22
	v_max3_f32 v51, v51, v24, v25
	v_max3_f32 v50, v50, v23, v42
	v_max3_f32 v51, v51, v44, v45
	v_max3_f32 v50, v50, v43, v26
	v_max3_f32 v51, v51, v28, v29
	v_max3_f32 v50, v50, v27, v46
	v_max3_f32 v51, v51, v48, v49
	v_max3_f32 v50, v50, v47, v30
	v_max3_f32 v51, v51, v32, v33
	v_max3_f32 v50, v50, v31, v51
	v_mov_b32_e32 v51, v50
	s_nop 1
	v_permlane32_swap_b32_e32 v50, v51
	v_max_f32_e32 v51, v51, v51
	v_max_f32_e32 v50, v50, v50
	v_max_f32_e32 v122, v50, v51
	v_sub_f32_e32 v18, v18, v122
	v_sub_f32_e32 v19, v19, v122
	v_sub_f32_e32 v34, v34, v122
	v_sub_f32_e32 v35, v35, v122
	v_exp_f32_e32 v34, v34
	v_exp_f32_e32 v127, v18
	v_exp_f32_e32 v18, v35
	v_exp_f32_e32 v128, v19
	v_sub_f32_e32 v20, v20, v122
	v_sub_f32_e32 v36, v36, v122
	v_exp_f32_e32 v19, v36
	v_exp_f32_e32 v129, v20
	v_sub_f32_e32 v21, v21, v122
	v_sub_f32_e32 v22, v22, v122
	v_sub_f32_e32 v23, v23, v122
	v_sub_f32_e32 v24, v24, v122
	v_sub_f32_e32 v25, v25, v122
	v_sub_f32_e32 v37, v37, v122
	v_sub_f32_e32 v38, v38, v122
	v_sub_f32_e32 v39, v39, v122
	v_sub_f32_e32 v40, v40, v122
	v_sub_f32_e32 v41, v41, v122
	v_exp_f32_e32 v20, v37
	v_exp_f32_e32 v130, v21
	v_exp_f32_e32 v21, v38
	v_exp_f32_e32 v38, v22
	v_exp_f32_e32 v22, v39
	v_exp_f32_e32 v39, v23
	v_exp_f32_e32 v23, v40
	v_exp_f32_e32 v40, v24
	v_exp_f32_e32 v131, v25
	v_add_f32_e32 v24, v34, v18
	v_add_f32_e32 v25, v127, v128
	v_exp_f32_e32 v41, v41
	v_cvt_pk_bf16_f32 v34, v34, v18
	v_add_f32_e32 v24, v24, v19
	v_add_f32_e32 v25, v25, v129
	v_cvt_pk_bf16_f32 v35, v19, v20
	v_add_f32_e32 v24, v24, v20
	v_add_f32_e32 v25, v25, v130
	v_cvt_pk_bf16_f32 v36, v21, v22
	v_cvt_pk_bf16_f32 v37, v23, v41
	v_add_f32_e32 v24, v21, v24
	v_add_f32_e32 v25, v38, v25
	v_sub_f32_e32 v42, v42, v122
	v_sub_f32_e32 v43, v43, v122
	v_sub_f32_e32 v44, v44, v122
	v_sub_f32_e32 v45, v45, v122
	v_sub_f32_e32 v46, v46, v122
	v_sub_f32_e32 v47, v47, v122
	v_sub_f32_e32 v48, v48, v122
	v_sub_f32_e32 v49, v49, v122
	v_add_f32_e32 v24, v22, v24
	v_add_f32_e32 v25, v39, v25
	v_sub_f32_e32 v26, v26, v122
	v_sub_f32_e32 v27, v27, v122
	v_sub_f32_e32 v28, v28, v122
	v_sub_f32_e32 v29, v29, v122
	v_sub_f32_e32 v30, v30, v122
	v_sub_f32_e32 v31, v31, v122
	v_sub_f32_e32 v32, v32, v122
	v_sub_f32_e32 v33, v33, v122
	v_exp_f32_e32 v42, v42
	v_exp_f32_e32 v43, v43
	v_exp_f32_e32 v44, v44
	v_exp_f32_e32 v45, v45
	v_exp_f32_e32 v136, v46
	v_exp_f32_e32 v138, v47
	v_exp_f32_e32 v140, v48
	v_exp_f32_e32 v142, v49
	v_exp_f32_e32 v132, v26
	v_exp_f32_e32 v133, v27
	v_exp_f32_e32 v134, v28
	v_exp_f32_e32 v135, v29
	v_exp_f32_e32 v137, v30
	v_exp_f32_e32 v139, v31
	v_exp_f32_e32 v141, v32
	v_exp_f32_e32 v143, v33
	v_add_f32_e32 v46, v23, v24
	v_add_f32_e32 v47, v40, v25
	v_mfma_f32_32x32x16_bf16 v[18:33], v[34:37], v[94:97], 0
	v_add_f32_e32 v171, 0, v122
	v_exp_f32_e64 v126, -v122
	v_cvt_pk_bf16_f32 v122, v42, v43
	v_cvt_pk_bf16_f32 v123, v44, v45
	v_cvt_pk_bf16_f32 v124, v136, v138
	v_cvt_pk_bf16_f32 v125, v140, v142
	v_cvt_pk_bf16_f32 v94, v127, v128
	v_cvt_pk_bf16_f32 v95, v129, v130
	s_waitcnt lgkmcnt(12)
	v_mfma_f32_32x32x16_bf16 v[18:33], v[122:125], v[90:93], v[18:33]
	v_cvt_pk_bf16_f32 v96, v38, v39
	v_cvt_pk_bf16_f32 v97, v40, v131
	v_cvt_pk_bf16_f32 v90, v132, v133
	v_add_f32_e32 v41, v41, v46
	s_waitcnt lgkmcnt(10)
	v_mfma_f32_32x32x16_bf16 v[18:33], v[94:97], v[86:89], v[18:33]
	v_add_f32_e32 v38, v42, v41
	v_add_f32_e32 v46, v131, v47
	v_cvt_pk_bf16_f32 v91, v134, v135
	v_cvt_pk_bf16_f32 v92, v137, v139
	v_cvt_pk_bf16_f32 v93, v141, v143
	v_add_f32_e32 v38, v43, v38
	v_add_f32_e32 v39, v132, v46
	s_waitcnt lgkmcnt(8)
	v_mfma_f32_32x32x16_bf16 v[18:33], v[90:93], v[82:85], v[18:33]
	v_add_f32_e32 v39, v133, v39
	v_add_f32_e32 v38, v44, v38
	s_lshl_b64 s[22:23], s[14:15], 6
	v_add_f32_e32 v82, v134, v39
	v_add_f32_e32 v83, v45, v38
	s_waitcnt lgkmcnt(6)
	v_mfma_f32_32x32x16_bf16 v[34:49], v[34:37], v[78:81], 0
	s_add_u32 s22, s13, s22
	v_add_f32_e32 v78, v135, v82
	v_add_f32_e32 v79, v136, v83
	v_add_f32_e32 v78, v137, v78
	s_waitcnt lgkmcnt(4)
	v_mfma_f32_32x32x16_bf16 v[34:49], v[122:125], v[74:77], v[34:49]
	v_xor_b32_e32 v50, 0x80000000, v171
	v_add_f32_e32 v74, v138, v79
	v_add_f32_e32 v75, v139, v78
	s_waitcnt lgkmcnt(2)
	v_mfma_f32_32x32x16_bf16 v[34:49], v[94:97], v[70:73], v[34:49]
	v_add_f32_e32 v74, v140, v74
	v_add_f32_e32 v75, v141, v75
	s_addc_u32 s23, s46, s23
	s_lshl_b64 s[54:55], s[14:15], 10
	v_mov_b32_e32 v51, v50
	v_mov_b32_e32 v52, v50
	v_mov_b32_e32 v53, v50
	s_waitcnt lgkmcnt(0)
	v_mfma_f32_32x32x16_bf16 v[34:49], v[90:93], v[66:69], v[34:49]
	v_mov_b32_e32 v54, v50
	v_mov_b32_e32 v55, v50
	v_mov_b32_e32 v56, v50
	v_mov_b32_e32 v57, v50
	v_mov_b32_e32 v58, v50
	v_mov_b32_e32 v59, v50
	v_mov_b32_e32 v60, v50
	v_mov_b32_e32 v61, v50
	v_mov_b32_e32 v62, v50
	v_mov_b32_e32 v63, v50
	v_mov_b32_e32 v64, v50
	v_mov_b32_e32 v65, v50
	s_add_u32 s0, s0, s54
	v_add_f32_e32 v70, v142, v74
	v_add_f32_e32 v71, v143, v75
	s_waitcnt vmcnt(0) lgkmcnt(0)
	s_barrier
	s_addc_u32 s53, s24, s55
	v_add_f32_e32 v173, v70, v71
	s_add_u32 s54, s26, s54
	v_fmac_f32_e32 v173, 0, v126
	s_addc_u32 s55, s27, s55
	s_mov_b64 s[24:25], 0x20000
	s_mov_b32 s49, s51
.LBB0_1476:
	s_mul_i32 s52, s49, 0x3000
	v_add_u32_e32 v66, s52, v182
	v_add_u32_e32 v67, v66, v184
	v_add_u32_e32 v66, v66, v189
	ds_read_b128 v[82:85], v67
	ds_read_b128 v[158:161], v67 offset:2048
	ds_read_b128 v[162:165], v66
	ds_read_b128 v[150:153], v66 offset:2048
	ds_read_b128 v[146:149], v67 offset:4096
	ds_read_b128 v[142:145], v67 offset:6144
	ds_read_b128 v[138:141], v66 offset:4096
	ds_read_b128 v[134:137], v66 offset:6144
	ds_read_b128 v[130:133], v67 offset:8192
	ds_read_b128 v[126:129], v67 offset:10240
	ds_read_b128 v[122:125], v66 offset:8192
	ds_read_b128 v[154:157], v66 offset:10240
	s_add_u32 s26, s54, s24
	s_addc_u32 s27, s55, s25
	s_xor_b32 s57, s49, 1
	s_mul_i32 s56, s57, 0x3000
	s_add_i32 s51, s56, s38
	s_mov_b32 s58, m0
	s_mov_b32 m0, s51
	s_nop 0
	global_load_lds_dwordx4 v1, s[26:27]
	s_mov_b32 m0, s58
	s_and_b64 vcc, exec, s[8:9]
	s_cbranch_vccnz .LBB0_1478
	s_add_i32 s26, s56, s39
	s_mov_b32 s27, m0
	s_mov_b32 m0, s26
	s_nop 0
	global_load_lds_dwordx4 v180, s[22:23]
	s_mov_b32 m0, s27
.LBB0_1478:
	s_add_u32 s26, s0, s24
	s_addc_u32 s27, s53, s25
	s_lshl_b32 s51, s57, 13
	s_add_i32 s58, s51, s43
	s_mov_b32 s59, m0
	s_mov_b32 m0, s58
	s_nop 0
	global_load_lds_dwordx4 v181, s[26:27]
	s_mov_b32 m0, s59
	s_waitcnt lgkmcnt(11)
	v_mfma_f32_32x32x16_bf16 v[66:81], v[82:85], v[98:101], v[50:65]
	s_lshl_b32 s58, s49, 13
	s_waitcnt lgkmcnt(10)
	v_mfma_f32_32x32x16_bf16 v[82:97], v[158:161], v[98:101], v[50:65]
	v_add_u32_e32 v158, s58, v183
	s_waitcnt lgkmcnt(9)
	v_mfma_f32_32x32x16_bf16 v[66:81], v[162:165], v[106:109], v[66:81]
	s_waitcnt lgkmcnt(8)
	v_mfma_f32_32x32x16_bf16 v[82:97], v[150:153], v[106:109], v[82:97]
	s_waitcnt lgkmcnt(7)
	v_mfma_f32_32x32x16_bf16 v[66:81], v[146:149], v[102:105], v[66:81]
	s_waitcnt lgkmcnt(6)
	v_mfma_f32_32x32x16_bf16 v[82:97], v[142:145], v[102:105], v[82:97]
	s_waitcnt lgkmcnt(5)
	v_mfma_f32_32x32x16_bf16 v[66:81], v[138:141], v[114:117], v[66:81]
	ds_read_b64_tr_b16 v[150:151], v158 offset:24576
	ds_read_b64_tr_b16 v[152:153], v158 offset:25088
	ds_read_b64_tr_b16 v[146:147], v158 offset:25600
	ds_read_b64_tr_b16 v[148:149], v158 offset:26112
	ds_read_b64_tr_b16 v[142:143], v158 offset:26624
	ds_read_b64_tr_b16 v[144:145], v158 offset:27136
	ds_read_b64_tr_b16 v[138:139], v158 offset:27648
	ds_read_b64_tr_b16 v[140:141], v158 offset:28160
	s_waitcnt lgkmcnt(12)
	v_mfma_f32_32x32x16_bf16 v[82:97], v[134:137], v[114:117], v[82:97]
	s_waitcnt lgkmcnt(11)
	v_mfma_f32_32x32x16_bf16 v[66:81], v[130:133], v[110:113], v[66:81]
	s_waitcnt lgkmcnt(10)
	v_mfma_f32_32x32x16_bf16 v[82:97], v[126:129], v[110:113], v[82:97]
	s_waitcnt lgkmcnt(9)
	v_mfma_f32_32x32x16_bf16 v[66:81], v[122:125], v[118:121], v[66:81]
	ds_read_b64_tr_b16 v[134:135], v158 offset:28672
	ds_read_b64_tr_b16 v[136:137], v158 offset:29184
	ds_read_b64_tr_b16 v[130:131], v158 offset:29696
	ds_read_b64_tr_b16 v[132:133], v158 offset:30208
	ds_read_b64_tr_b16 v[126:127], v158 offset:30720
	ds_read_b64_tr_b16 v[128:129], v158 offset:31232
	ds_read_b64_tr_b16 v[122:123], v158 offset:31744
	ds_read_b64_tr_b16 v[124:125], v158 offset:32256
	s_waitcnt lgkmcnt(14)
	v_mfma_f32_32x32x16_bf16 v[82:97], v[154:157], v[118:121], v[82:97]
	s_nop 1
	v_max_f32_e32 v154, v67, v67
	v_max_f32_e32 v155, v66, v66
	v_max_f32_e32 v154, v155, v154
	s_nop 6
	v_max3_f32 v155, v68, v69, v83
	v_max3_f32 v154, v154, v82, v84
	v_max3_f32 v154, v154, v85, v70
	v_max3_f32 v155, v155, v72, v73
	v_max3_f32 v154, v154, v71, v86
	v_max3_f32 v155, v155, v88, v89
	v_max3_f32 v154, v154, v87, v74
	v_max3_f32 v155, v155, v76, v77
	v_max3_f32 v154, v154, v75, v90
	v_max3_f32 v155, v155, v92, v93
	v_max3_f32 v154, v154, v91, v78
	v_max3_f32 v155, v155, v80, v81
	v_max3_f32 v154, v154, v79, v94
	v_max3_f32 v155, v155, v96, v97
	v_max3_f32 v154, v154, v95, v155
	v_mov_b32_e32 v155, v154
	s_nop 1
	v_permlane32_swap_b32_e32 v154, v155
	v_max_f32_e32 v155, v155, v155
	v_max_f32_e32 v154, v154, v154
	v_max_f32_e32 v154, v154, v155
	v_cmp_lt_f32_e32 vcc, s47, v154
	s_cbranch_vccz .LBB0_1482
	v_max_f32_e32 v50, v154, v154
	v_max_f32_e32 v154, 0, v50
	v_exp_f32_e64 v155, -v154
	v_add_f32_e32 v171, v171, v154
	v_xor_b32_e32 v50, 0x80000000, v171
	v_mov_b32_e32 v51, v50
	v_mov_b32_e32 v52, v50
	v_mov_b32_e32 v53, v50
	v_mov_b32_e32 v54, v50
	v_mov_b32_e32 v55, v50
	v_mov_b32_e32 v56, v50
	v_mov_b32_e32 v57, v50
	v_mov_b32_e32 v58, v50
	v_mov_b32_e32 v59, v50
	v_mov_b32_e32 v60, v50
	v_mov_b32_e32 v61, v50
	v_mov_b32_e32 v62, v50
	v_mov_b32_e32 v63, v50
	v_mov_b32_e32 v64, v50
	v_mov_b32_e32 v65, v50
	s_and_saveexec_b64 s[26:27], s[6:7]
	ds_write_b32 v186, v155 offset:40960
	s_or_b64 exec, exec, s[26:27]
	v_add_u32_e32 v164, s42, v187
	ds_read_b128 v[156:159], v164 offset:41024
	ds_read_b128 v[160:163], v164 offset:41056
	ds_read_b128 v[196:199], v164 offset:40960
	ds_read_b128 v[200:203], v164 offset:40992
	v_pk_add_f32 v[66:67], v[66:67], v[154:155] op_sel_hi:[1,0] neg_lo:[0,1] neg_hi:[0,1]
	v_pk_add_f32 v[82:83], v[82:83], v[154:155] op_sel_hi:[1,0] neg_lo:[0,1] neg_hi:[0,1]
	v_pk_add_f32 v[68:69], v[68:69], v[154:155] op_sel_hi:[1,0] neg_lo:[0,1] neg_hi:[0,1]
	v_pk_add_f32 v[84:85], v[84:85], v[154:155] op_sel_hi:[1,0] neg_lo:[0,1] neg_hi:[0,1]
	v_pk_add_f32 v[70:71], v[70:71], v[154:155] op_sel_hi:[1,0] neg_lo:[0,1] neg_hi:[0,1]
	v_pk_add_f32 v[86:87], v[86:87], v[154:155] op_sel_hi:[1,0] neg_lo:[0,1] neg_hi:[0,1]
	v_pk_add_f32 v[72:73], v[72:73], v[154:155] op_sel_hi:[1,0] neg_lo:[0,1] neg_hi:[0,1]
	v_pk_add_f32 v[88:89], v[88:89], v[154:155] op_sel_hi:[1,0] neg_lo:[0,1] neg_hi:[0,1]
	v_pk_add_f32 v[74:75], v[74:75], v[154:155] op_sel_hi:[1,0] neg_lo:[0,1] neg_hi:[0,1]
	v_pk_add_f32 v[90:91], v[90:91], v[154:155] op_sel_hi:[1,0] neg_lo:[0,1] neg_hi:[0,1]
	v_pk_add_f32 v[76:77], v[76:77], v[154:155] op_sel_hi:[1,0] neg_lo:[0,1] neg_hi:[0,1]
	v_pk_add_f32 v[92:93], v[92:93], v[154:155] op_sel_hi:[1,0] neg_lo:[0,1] neg_hi:[0,1]
	v_pk_add_f32 v[78:79], v[78:79], v[154:155] op_sel_hi:[1,0] neg_lo:[0,1] neg_hi:[0,1]
	v_pk_add_f32 v[94:95], v[94:95], v[154:155] op_sel_hi:[1,0] neg_lo:[0,1] neg_hi:[0,1]
	v_pk_add_f32 v[80:81], v[80:81], v[154:155] op_sel_hi:[1,0] neg_lo:[0,1] neg_hi:[0,1]
	v_pk_add_f32 v[96:97], v[96:97], v[154:155] op_sel_hi:[1,0] neg_lo:[0,1] neg_hi:[0,1]
	v_mul_f32_e32 v173, v173, v155
	s_waitcnt lgkmcnt(2)
	v_pk_mul_f32 v[30:31], v[30:31], v[160:161]
	v_pk_mul_f32 v[26:27], v[26:27], v[156:157]
	s_waitcnt lgkmcnt(0)
	v_pk_mul_f32 v[22:23], v[22:23], v[200:201]
	v_pk_mul_f32 v[32:33], v[32:33], v[162:163]
	v_pk_mul_f32 v[28:29], v[28:29], v[158:159]
	v_pk_mul_f32 v[24:25], v[24:25], v[202:203]
	v_pk_mul_f32 v[20:21], v[20:21], v[198:199]
	v_pk_mul_f32 v[18:19], v[18:19], v[196:197]
	v_pk_mul_f32 v[46:47], v[46:47], v[160:161]
	v_pk_mul_f32 v[42:43], v[42:43], v[156:157]
	v_pk_mul_f32 v[38:39], v[38:39], v[200:201]
	v_pk_mul_f32 v[48:49], v[48:49], v[162:163]
	v_pk_mul_f32 v[44:45], v[44:45], v[158:159]
	v_pk_mul_f32 v[40:41], v[40:41], v[202:203]
	v_pk_mul_f32 v[36:37], v[36:37], v[198:199]
	v_pk_mul_f32 v[34:35], v[34:35], v[196:197]

.LBB0_1484:
	v_add_u32_e32 v66, s56, v182
	v_add_u32_e32 v67, v66, v184
	v_add_u32_e32 v66, v66, v189
	ds_read_b128 v[150:153], v67
	ds_read_b128 v[142:145], v67 offset:2048
	ds_read_b128 v[146:149], v66
	ds_read_b128 v[138:141], v66 offset:2048
	ds_read_b128 v[134:137], v67 offset:4096
	ds_read_b128 v[130:133], v67 offset:6144
	ds_read_b128 v[126:129], v66 offset:4096
	ds_read_b128 v[122:125], v66 offset:6144
	ds_read_b128 v[94:97], v67 offset:8192
	ds_read_b128 v[90:93], v67 offset:10240
	ds_read_b128 v[86:89], v66 offset:8192
	ds_read_b128 v[82:85], v66 offset:10240
	s_add_i32 s26, s50, 1
	s_cmp_lt_u32 s26, s28
	s_cselect_b64 s[22:23], -1, 0
	s_and_b64 s[24:25], s[22:23], exec
	s_cselect_b32 s0, s26, s50
	s_lshl_b32 s50, s0, s44
	s_add_i32 s50, s50, s29
	s_bfe_u32 s27, s50, 0x30003
	s_ashr_i32 s24, s50, 6
	s_ashr_i32 s25, s24, 31
	s_lshl_b32 s0, s27, 6
	s_cmp_ge_u32 s26, s28
	s_cbranch_scc1 .LBB0_1488
	s_lshl_b64 s[54:55], s[24:25], 21
	s_add_u32 s54, s10, s54
	s_addc_u32 s55, s11, s55
	s_lshl_b32 s53, s0, 1
	s_add_u32 s54, s54, s53
	s_addc_u32 s55, s55, 0
	s_add_i32 s56, s52, s38
	s_and_b64 vcc, exec, s[8:9]
	s_mov_b32 s8, m0
	s_mov_b32 m0, s56
	s_nop 0
	global_load_lds_dwordx4 v1, s[54:55]
	s_mov_b32 m0, s8
	s_cbranch_vccnz .LBB0_1487
	s_lshl_b64 s[8:9], s[24:25], 17
	s_add_u32 s8, s16, s8
	s_addc_u32 s9, s17, s9
	s_add_i32 s52, s52, s39
	s_mov_b32 s54, m0
	s_mov_b32 m0, s52
	s_nop 0
	global_load_lds_dwordx4 v180, s[8:9]
	s_mov_b32 m0, s54
.LBB0_1487:
	s_lshl_b64 s[8:9], s[24:25], 20
	s_lshl_b64 s[8:9], s[8:9], 1
	s_add_u32 s8, s34, s8
	s_addc_u32 s9, s35, s9
	s_add_u32 s8, s8, s53
	s_addc_u32 s9, s9, 0
	s_add_i32 s52, s58, s43
	s_mov_b32 s53, m0
	s_mov_b32 m0, s52
	s_nop 0
	global_load_lds_dwordx4 v181, s[8:9]
	s_mov_b32 m0, s53
